# shift-output copy spread over 243 wave tasks (was 9 waves x 54 dependent round trips)
# speedup vs baseline: 1.0076x; 1.0009x over previous
; __device__ __forceinline__ float bf2f(bf16 x) { return __uint_as_float(((unsigned)x) << 16); }
; __device__ __forceinline__ void rw_lora_in(Frame& F) {
;     ...
;     for (int q = F.gw; q < 9; q += F.NGW) { const int row = q == 0 ? MPR - 1 : MPR + 16 * (q - 1) + 15; float* o = q == 0 ? F.out + O_SHP : F.out + O_SHS + (size_t)(q - 1) * DRIN;
;         for (int c = F.lane; c < DRIN; c += 64) o[c] = bf2f(ZR[(size_t)row * LDZR + c]); }
.LBB0_667:
	s_cmpk_gt_i32 s94, 242
	s_cbranch_scc1 .LBB0_679
	s_mov_b32 s4, s94
	v_lshlrev_b32_e32 v1, 2, v178
	v_lshlrev_b32_e32 v2, 3, v178
	v_lshlrev_b32_e32 v3, 4, v178
.Lsh_task:
	s_mul_i32 s5, s4, 2428
	s_lshr_b32 s5, s5, 16
	s_mul_i32 s6, s5, 27
	s_sub_i32 s6, s4, s6
	s_lshl_b32 s7, s5, 4
	s_add_i32 s7, s7, 0x3fff
	s_mul_i32 s8, s7, 13824
	s_lshl_b32 s9, s6, 9
	s_add_u32 s8, s8, s9
	s_add_u32 s10, s18, s8
	s_addc_u32 s11, s19, 0
	s_cmp_eq_u32 s5, 0
	s_cbranch_scc1 .Lsh_p
	s_sub_i32 s12, s5, 1
	s_mul_i32 s12, s12, 27520
	s_add_u32 s12, s12, 0x10f86b80
	s_branch .Lsh_d
.Lsh_p:
	s_mov_b32 s12, 0x10380000
.Lsh_d:
	s_lshl_b32 s13, s6, 10
	s_add_u32 s12, s12, s13
	s_add_u32 s14, s88, s12
	s_addc_u32 s15, s89, 0
	s_lshl_b32 s13, s6, 8
	s_sub_i32 s13, 6880, s13
	v_cmp_gt_u32_e32 vcc, s13, v1
	s_and_saveexec_b64 s[16:17], vcc
	global_load_dwordx2 v[4:5], v2, s[10:11]
	s_waitcnt vmcnt(0)
	v_lshlrev_b32_e32 v6, 16, v4
	v_and_b32_e32 v7, 0xffff0000, v4
	v_lshlrev_b32_e32 v8, 16, v5
	v_and_b32_e32 v9, 0xffff0000, v5
	global_store_dwordx4 v3, v[6:9], s[14:15]
	s_or_b64 exec, exec, s[16:17]
	s_add_i32 s4, s4, s92
	s_cmpk_lt_i32 s4, 243
	s_cbranch_scc1 .Lsh_task
